# LRU: next-chunk loads prefetched after barrier 1 with immediate-offset addressing, pruned top-of-chunk block for chunks > 0; HGRN loads interleaved in part A
# speedup vs baseline: 1.0083x; 1.0018x over previous
; __device__ __forceinline__ bf16_t f2bf(float f) { return (bf16_t)(cvt_pk_bf16(f, 0.f) & 0xffffu); }
; __device__ __forceinline__ float bf2f(bf16_t b) { return __uint_as_float(((unsigned)b) << 16); }
; __device__ __forceinline__ void lru_item(LAS unsigned char* lds, int item, const bf16_t* XB, const bf16_t* GB, const float* conv_w, const float* conv_b, const bf16_t* WLA, const bf16_t* WLX,
;                                          const float* ba, const float* bx, const float* lam, bf16_t* YAB) {
;     ...
;         { const int t0 = c * 64 + part * 16;
; #pragma unroll
;           for (int i = 0; i < 19; ++i) { const int t = t0 - 3 + i; xin[i] = (t >= 0) ? bf2f(XB[(row0 + t) * HW + colc]) : 0.f; } }
;         float gbv[8];
; #pragma unroll
;         for (int i = 0; i < 8; ++i) gbv[i] = bf2f(GB[(row0 + (size_t)c * 64 + g * 8 + i) * HW + colo]);
; #pragma unroll
;         for (int i = 0; i < 16; ++i) {
;             const float xc = cb + w0 * xin[i + 3] + w1 * xin[i + 2] + w2 * xin[i + 1] + w3 * xin[i];
;             XC[(part * 16 + i) * 136 + ch] = f2bf(xc);
;             if (own) XCF[(part * 16 + i) * 65 + (ch & 63)] = xc;
;         }
.Llru_top_b:
	s_waitcnt vmcnt(8)
	s_lshl_b32 s96, s61, 6
	s_mov_b64 s[0:1], -1
	s_mov_b64 s[38:39], -1
	v_add_u32_e32 v26, s96, v95
	v_or_b32_e32 v98, 1, v26
	v_or_b32_e32 v99, 2, v26
	v_or_b32_e32 v100, 3, v26
	v_or_b32_e32 v101, 4, v26
	v_or_b32_e32 v102, 5, v26
	v_or_b32_e32 v103, 6, v26
	v_or_b32_e32 v168, 7, v26
	v_mov_b32_e32 v231, v194
	v_mov_b32_e32 v246, v195
	v_mov_b32_e32 v247, v196
	v_mov_b32_e32 v0, v197
	v_mov_b32_e32 v1, v198
	v_mov_b32_e32 v181, v199
	v_mov_b32_e32 v186, v200
	v_mov_b32_e32 v184, v201
	v_mov_b32_e32 v185, v202
	v_mov_b32_e32 v182, v203
	v_mov_b32_e32 v183, v204
	v_mov_b32_e32 v14, v205
	v_mov_b32_e32 v15, v206
	v_mov_b32_e32 v12, v207
	v_mov_b32_e32 v13, v208
	v_mov_b32_e32 v10, v209
	v_mov_b32_e32 v11, v210
	v_mov_b32_e32 v8, v211
	v_mov_b32_e32 v9, v212
	v_mov_b32_e32 v169, v213
	v_mov_b32_e32 v170, v214
	v_mov_b32_e32 v171, v215
	v_mov_b32_e32 v172, v216
	v_mov_b32_e32 v173, v217
	v_mov_b32_e32 v174, v218
	v_mov_b32_e32 v175, v219
	v_mov_b32_e32 v180, v220

; __device__ __forceinline__ float bf2f(bf16_t b) { return __uint_as_float(((unsigned)b) << 16); }
; __device__ __forceinline__ void lru_item(LAS unsigned char* lds, int item, const bf16_t* XB, const bf16_t* GB, const float* conv_w, const float* conv_b, const bf16_t* WLA, const bf16_t* WLX,
;                                          const float* ba, const float* bx, const float* lam, bf16_t* YAB) {
;     ...
;         { const int t0 = c * 64 + part * 16;
; #pragma unroll
;           for (int i = 0; i < 19; ++i) { const int t = t0 - 3 + i; xin[i] = (t >= 0) ? bf2f(XB[(row0 + t) * HW + colc]) : 0.f; } }
;         float gbv[8];
; #pragma unroll
;         for (int i = 0; i < 8; ++i) gbv[i] = bf2f(GB[(row0 + (size_t)c * 64 + g * 8 + i) * HW + colo]);
.LBB0_675:
	s_or_b64 exec, exec, s[0:1]
	v_cvt_pk_bf16_f32 v0, v4, s0
	ds_write_b16 v151, v0
	s_waitcnt lgkmcnt(0)
	s_barrier
	s_cmp_eq_u32 s61, 63
	s_cbranch_scc1 .Llru_nopf
	s_lshl_b32 s98, s61, 6
	s_add_i32 s98, s98, 64
	v_add_u32_e32 v230, s98, v41
	v_mov_b32_e32 v229, 0
	v_add3_u32 v228, s60, v230, 2
	v_lshlrev_b64 v[226:227], 11, v[228:229]
	v_lshl_add_u64 v[226:227], v[20:21], 0, v[226:227]
	s_mov_b64 s[100:101], 0x2000
	global_load_ushort v194, v[226:227], off offset:-4096
	global_load_ushort v195, v[226:227], off offset:-2048
	global_load_ushort v196, v[226:227], off
	global_load_ushort v197, v[226:227], off offset:2048
	v_lshl_add_u64 v[226:227], v[226:227], 0, s[100:101]
	global_load_ushort v198, v[226:227], off offset:-4096
	global_load_ushort v199, v[226:227], off offset:-2048
	global_load_ushort v200, v[226:227], off
	global_load_ushort v201, v[226:227], off offset:2048
	v_lshl_add_u64 v[226:227], v[226:227], 0, s[100:101]
	global_load_ushort v202, v[226:227], off offset:-4096
	global_load_ushort v203, v[226:227], off offset:-2048
	global_load_ushort v204, v[226:227], off
	global_load_ushort v205, v[226:227], off offset:2048
	v_lshl_add_u64 v[226:227], v[226:227], 0, s[100:101]
	global_load_ushort v206, v[226:227], off offset:-4096
	global_load_ushort v207, v[226:227], off offset:-2048
	global_load_ushort v208, v[226:227], off
	global_load_ushort v209, v[226:227], off offset:2048
	v_lshl_add_u64 v[226:227], v[226:227], 0, s[100:101]
	global_load_ushort v210, v[226:227], off offset:-4096
	global_load_ushort v211, v[226:227], off offset:-2048
	global_load_ushort v212, v[226:227], off
	v_add3_u32 v228, s98, v95, 2
	v_lshl_or_b32 v227, v228, 11, v97
	global_load_ushort v213, v227, s[68:69] offset:-4096
	global_load_ushort v214, v227, s[68:69] offset:-2048
	global_load_ushort v215, v227, s[68:69]
	global_load_ushort v216, v227, s[68:69] offset:2048
	v_add_u32_e32 v227, 0x2000, v227
	global_load_ushort v217, v227, s[68:69] offset:-4096
	global_load_ushort v218, v227, s[68:69] offset:-2048
	global_load_ushort v219, v227, s[68:69]
	global_load_ushort v220, v227, s[68:69] offset:2048
